# PEER apply: gelu*gate folded into the V sweep's group setup (no separate pass)
# baseline (speedup 1.0000x reference)
; __device__ __forceinline__ float geluf_(float x) { return 0.5f * x * (1.0f + tanhf(0.7978845608028654f * (x + 0.044715f * x * x * x))); }
; __device__ __forceinline__ void ph_peer_apply(const Params& P, int layer, float* xlat, float* xctx_in, float* xctx_out, int nrows, bool write_next, char* smem, float* xlat_out = nullptr) {
;     ...
;       PB_DOT(bufB, gq + 1);
;     }
;     a0 = geluf_(a0) * g0; a1 = geluf_(a1) * g1;
;     float o[32];
; #pragma unroll
;     for (int j = 0; j < 32; ++j) o[j] = 0.f;
;     ...
;     PB_LOAD(bufA, tv, 0);
.Lau0_s1end:
	s_waitcnt vmcnt(0) lgkmcnt(0)
	s_add_u32 s16, s4, 0x7c7c000
	s_addc_u32 s17, s5, 0
	s_and_b32 s17, s17, 0xffff
	s_mov_b32 s18, 0x1900000
	s_mov_b32 s19, 0x20000
	s_mov_b32 s62, 0
	s_mov_b32 s1, s13

; __device__ __forceinline__ float geluf_(float x) { return 0.5f * x * (1.0f + tanhf(0.7978845608028654f * (x + 0.044715f * x * x * x))); }
; __device__ __forceinline__ void ph_peer_apply(const Params& P, int layer, float* xlat, float* xctx_in, float* xctx_out, int nrows, bool write_next, char* smem, float* xlat_out = nullptr) {
;     ...
;     const int id0 = seli[(size_t)row * NSEL + lane], id1 = seli[(size_t)row * NSEL + 64 + lane];
;     const float g0 = selg[(size_t)row * NSEL + lane], g1 = selg[(size_t)row * NSEL + 64 + lane];
;     ...
;     a0 = geluf_(a0) * g0; a1 = geluf_(a1) * g1;
.Lav0_group:
	s_sub_u32 s57, s62, s51
	s_min_u32 s57, s57, 4
	s_add_u32 s1, s51, 0
	s_lshl_b32 s31, s1, 9
	s_mul_i32 s1, s1, s44
	s_add_u32 s1, s1, s13
	s_lshl_b32 s15, s1, 9
	s_add_u32 s22, s4, 0x1404c000
	s_addc_u32 s23, s5, 0
	s_add_u32 s22, s22, s15
	s_addc_u32 s23, s23, 0
	global_load_dword v36, v226, s[22:23]
	global_load_dword v37, v226, s[22:23] offset:256
	s_add_u32 s24, s4, 0x1508c000
	s_addc_u32 s25, s5, 0
	s_add_u32 s24, s24, s15
	s_addc_u32 s25, s25, 0
	global_load_dword v114, v226, s[24:25]
	global_load_dword v115, v226, s[24:25] offset:256
	v_add_u32_e32 v229, s31, v228
	ds_read_b32 v112, v229
	ds_read_b32 v113, v229 offset:256
	s_cmp_le_u32 s57, 1
	s_cbranch_scc1 .Lav0_ldd
	s_add_u32 s1, s51, 1
	s_lshl_b32 s31, s1, 9
	s_mul_i32 s1, s1, s44
	s_add_u32 s1, s1, s13
	s_lshl_b32 s15, s1, 9
	s_add_u32 s22, s4, 0x1404c000
	s_addc_u32 s23, s5, 0
	s_add_u32 s22, s22, s15
	s_addc_u32 s23, s23, 0
	global_load_dword v38, v226, s[22:23]
	global_load_dword v39, v226, s[22:23] offset:256
	s_add_u32 s24, s4, 0x1508c000
	s_addc_u32 s25, s5, 0
	s_add_u32 s24, s24, s15
	s_addc_u32 s25, s25, 0
	global_load_dword v116, v226, s[24:25]
	global_load_dword v117, v226, s[24:25] offset:256
	v_add_u32_e32 v229, s31, v228
	ds_read_b32 v146, v229
	ds_read_b32 v147, v229 offset:256
	s_cmp_le_u32 s57, 2
	s_cbranch_scc1 .Lav0_ldd
	s_add_u32 s1, s51, 2
	s_lshl_b32 s31, s1, 9
	s_mul_i32 s1, s1, s44
	s_add_u32 s1, s1, s13
	s_lshl_b32 s15, s1, 9
	s_add_u32 s22, s4, 0x1404c000
	s_addc_u32 s23, s5, 0
	s_add_u32 s22, s22, s15
	s_addc_u32 s23, s23, 0
	global_load_dword v40, v226, s[22:23]
	global_load_dword v41, v226, s[22:23] offset:256
	s_add_u32 s24, s4, 0x1508c000
	s_addc_u32 s25, s5, 0
	s_add_u32 s24, s24, s15
	s_addc_u32 s25, s25, 0
	global_load_dword v118, v226, s[24:25]
	global_load_dword v119, v226, s[24:25] offset:256
	v_add_u32_e32 v229, s31, v228
	ds_read_b32 v230, v229
	ds_read_b32 v231, v229 offset:256
	s_cmp_le_u32 s57, 3
	s_cbranch_scc1 .Lav0_ldd
	s_add_u32 s1, s51, 3
	s_lshl_b32 s31, s1, 9
	s_mul_i32 s1, s1, s44
	s_add_u32 s1, s1, s13
	s_lshl_b32 s15, s1, 9
	s_add_u32 s22, s4, 0x1404c000
	s_addc_u32 s23, s5, 0
	s_add_u32 s22, s22, s15
	s_addc_u32 s23, s23, 0
	global_load_dword v42, v226, s[22:23]
	global_load_dword v43, v226, s[22:23] offset:256
	s_add_u32 s24, s4, 0x1508c000
	s_addc_u32 s25, s5, 0
	s_add_u32 s24, s24, s15
	s_addc_u32 s25, s25, 0
	global_load_dword v120, v226, s[24:25]
	global_load_dword v121, v226, s[24:25] offset:256
	v_add_u32_e32 v229, s31, v228
	ds_read_b32 v252, v229
	ds_read_b32 v253, v229 offset:256
; __device__ __forceinline__ float geluf_(float x) { return 0.5f * x * (1.0f + tanhf(0.7978845608028654f * (x + 0.044715f * x * x * x))); }
; __device__ __forceinline__ void ph_peer_apply(const Params& P, int layer, float* xlat, float* xctx_in, float* xctx_out, int nrows, bool write_next, char* smem, float* xlat_out = nullptr) {
;     ...
;     a0 = geluf_(a0) * g0; a1 = geluf_(a1) * g1;
;     float o[32];
; #pragma unroll
;     for (int j = 0; j < 32; ++j) o[j] = 0.f;
.Lav0_ldd:
	v_mov_b32_e32 v160, 0
	v_mov_b32_e32 v161, 0
	v_mov_b32_e32 v162, 0
	v_mov_b32_e32 v163, 0
	v_mov_b32_e32 v164, 0
	v_mov_b32_e32 v165, 0
	v_mov_b32_e32 v166, 0
	v_mov_b32_e32 v167, 0
	v_mov_b32_e32 v168, 0
	v_mov_b32_e32 v169, 0
	v_mov_b32_e32 v170, 0
	v_mov_b32_e32 v171, 0
	v_mov_b32_e32 v172, 0
	v_mov_b32_e32 v173, 0
	v_mov_b32_e32 v174, 0
	v_mov_b32_e32 v175, 0
	v_mov_b32_e32 v176, 0
	v_mov_b32_e32 v177, 0
	v_mov_b32_e32 v178, 0
	v_mov_b32_e32 v179, 0
	v_mov_b32_e32 v180, 0
	v_mov_b32_e32 v181, 0
	v_mov_b32_e32 v182, 0
	v_mov_b32_e32 v183, 0
	v_mov_b32_e32 v184, 0
	v_mov_b32_e32 v185, 0
	v_mov_b32_e32 v186, 0
	v_mov_b32_e32 v187, 0
	v_mov_b32_e32 v188, 0
	v_mov_b32_e32 v189, 0
	v_mov_b32_e32 v190, 0
	v_mov_b32_e32 v191, 0
	v_mov_b32_e32 v4, 0
	v_mov_b32_e32 v5, 0
	v_mov_b32_e32 v6, 0
	v_mov_b32_e32 v7, 0
	v_mov_b32_e32 v8, 0
	v_mov_b32_e32 v9, 0
	v_mov_b32_e32 v10, 0
	v_mov_b32_e32 v11, 0
	v_mov_b32_e32 v12, 0
	v_mov_b32_e32 v13, 0
	v_mov_b32_e32 v14, 0
	v_mov_b32_e32 v15, 0
	v_mov_b32_e32 v16, 0
	v_mov_b32_e32 v17, 0
	v_mov_b32_e32 v18, 0
	v_mov_b32_e32 v19, 0
	v_mov_b32_e32 v20, 0
	v_mov_b32_e32 v21, 0
	v_mov_b32_e32 v22, 0
	v_mov_b32_e32 v23, 0
	v_mov_b32_e32 v24, 0
	v_mov_b32_e32 v25, 0
	v_mov_b32_e32 v26, 0
	v_mov_b32_e32 v27, 0
	v_mov_b32_e32 v28, 0
	v_mov_b32_e32 v29, 0
	v_mov_b32_e32 v30, 0
	v_mov_b32_e32 v31, 0
	v_mov_b32_e32 v32, 0
	v_mov_b32_e32 v33, 0
	v_mov_b32_e32 v34, 0
	v_mov_b32_e32 v35, 0
	v_mov_b32_e32 v192, 0
	v_mov_b32_e32 v193, 0
	v_mov_b32_e32 v194, 0
	v_mov_b32_e32 v195, 0
	v_mov_b32_e32 v196, 0
	v_mov_b32_e32 v197, 0
	v_mov_b32_e32 v198, 0
	v_mov_b32_e32 v199, 0
	v_mov_b32_e32 v200, 0
	v_mov_b32_e32 v201, 0
	v_mov_b32_e32 v202, 0
	v_mov_b32_e32 v203, 0
	v_mov_b32_e32 v204, 0
	v_mov_b32_e32 v205, 0
	v_mov_b32_e32 v206, 0
	v_mov_b32_e32 v207, 0
	v_mov_b32_e32 v208, 0
	v_mov_b32_e32 v209, 0
	v_mov_b32_e32 v210, 0
	v_mov_b32_e32 v211, 0
	v_mov_b32_e32 v212, 0
	v_mov_b32_e32 v213, 0
	v_mov_b32_e32 v214, 0
	v_mov_b32_e32 v215, 0
	v_mov_b32_e32 v216, 0
	v_mov_b32_e32 v217, 0
	v_mov_b32_e32 v218, 0
	v_mov_b32_e32 v219, 0
	v_mov_b32_e32 v220, 0
	v_mov_b32_e32 v221, 0
	v_mov_b32_e32 v222, 0
	v_mov_b32_e32 v223, 0
	v_mov_b32_e32 v148, 0
	v_mov_b32_e32 v149, 0
	v_mov_b32_e32 v150, 0
	v_mov_b32_e32 v151, 0
	v_mov_b32_e32 v152, 0
	v_mov_b32_e32 v153, 0
	v_mov_b32_e32 v154, 0
	v_mov_b32_e32 v155, 0
	v_mov_b32_e32 v156, 0
	v_mov_b32_e32 v157, 0
	v_mov_b32_e32 v158, 0
	v_mov_b32_e32 v159, 0
	v_mov_b32_e32 v232, 0
	v_mov_b32_e32 v233, 0
	v_mov_b32_e32 v234, 0
	v_mov_b32_e32 v235, 0
	v_mov_b32_e32 v236, 0
	v_mov_b32_e32 v237, 0
	v_mov_b32_e32 v238, 0
	v_mov_b32_e32 v239, 0
	v_mov_b32_e32 v240, 0
	v_mov_b32_e32 v241, 0
	v_mov_b32_e32 v242, 0
	v_mov_b32_e32 v243, 0
	v_mov_b32_e32 v244, 0
	v_mov_b32_e32 v245, 0
	v_mov_b32_e32 v246, 0
	v_mov_b32_e32 v247, 0
	v_mov_b32_e32 v248, 0
	v_mov_b32_e32 v249, 0
	v_mov_b32_e32 v250, 0
	v_mov_b32_e32 v251, 0
	s_mov_b64 s[52:53], 0
	s_mov_b64 s[54:55], 0
	s_mov_b32 s61, 1
	s_mov_b32 s59, -1
	s_mov_b32 s58, 0
	s_mov_b32 s48, 0
	s_mov_b32 s49, 0
	s_waitcnt vmcnt(0) lgkmcnt(0)
	v_mul_f32_e32 v122, v112, v112
	v_mul_f32_e32 v122, v122, v112
	v_fmamk_f32 v122, v122, 0x3d372713, v112
	v_mul_f32_e32 v122, 0xc0135761, v122
	v_exp_f32_e32 v122, v122
	s_nop 0
	v_add_f32_e32 v122, 1.0, v122
	v_rcp_f32_e32 v122, v122
	s_nop 0
	v_mul_f32_e32 v122, v122, v112
	v_mul_f32_e32 v112, v122, v114
	v_mul_f32_e32 v122, v113, v113
	v_mul_f32_e32 v122, v122, v113
	v_fmamk_f32 v122, v122, 0x3d372713, v113
	v_mul_f32_e32 v122, 0xc0135761, v122
	v_exp_f32_e32 v122, v122
	s_nop 0
	v_add_f32_e32 v122, 1.0, v122
	v_rcp_f32_e32 v122, v122
	s_nop 0
	v_mul_f32_e32 v122, v122, v113
	v_mul_f32_e32 v113, v122, v115
	v_mul_f32_e32 v122, v146, v146
	v_mul_f32_e32 v122, v122, v146
	v_fmamk_f32 v122, v122, 0x3d372713, v146
	v_mul_f32_e32 v122, 0xc0135761, v122
	v_exp_f32_e32 v122, v122
	s_nop 0
	v_add_f32_e32 v122, 1.0, v122
	v_rcp_f32_e32 v122, v122
	s_nop 0
	v_mul_f32_e32 v122, v122, v146
	v_mul_f32_e32 v146, v122, v116
	v_mul_f32_e32 v122, v147, v147
	v_mul_f32_e32 v122, v122, v147
	v_fmamk_f32 v122, v122, 0x3d372713, v147
	v_mul_f32_e32 v122, 0xc0135761, v122
	v_exp_f32_e32 v122, v122
	s_nop 0
	v_add_f32_e32 v122, 1.0, v122
	v_rcp_f32_e32 v122, v122
	s_nop 0
	v_mul_f32_e32 v122, v122, v147
	v_mul_f32_e32 v147, v122, v117
	v_mul_f32_e32 v122, v230, v230
	v_mul_f32_e32 v122, v122, v230
	v_fmamk_f32 v122, v122, 0x3d372713, v230
	v_mul_f32_e32 v122, 0xc0135761, v122
	v_exp_f32_e32 v122, v122
	s_nop 0
	v_add_f32_e32 v122, 1.0, v122
	v_rcp_f32_e32 v122, v122
	s_nop 0
	v_mul_f32_e32 v122, v122, v230
	v_mul_f32_e32 v230, v122, v118
	v_mul_f32_e32 v122, v231, v231
	v_mul_f32_e32 v122, v122, v231
	v_fmamk_f32 v122, v122, 0x3d372713, v231
	v_mul_f32_e32 v122, 0xc0135761, v122
	v_exp_f32_e32 v122, v122
	s_nop 0
	v_add_f32_e32 v122, 1.0, v122
	v_rcp_f32_e32 v122, v122
	s_nop 0
	v_mul_f32_e32 v122, v122, v231
	v_mul_f32_e32 v231, v122, v119
	v_mul_f32_e32 v122, v252, v252
	v_mul_f32_e32 v122, v122, v252
	v_fmamk_f32 v122, v122, 0x3d372713, v252
	v_mul_f32_e32 v122, 0xc0135761, v122
	v_exp_f32_e32 v122, v122
	s_nop 0
	v_add_f32_e32 v122, 1.0, v122
	v_rcp_f32_e32 v122, v122
	s_nop 0
	v_mul_f32_e32 v122, v122, v252
	v_mul_f32_e32 v252, v122, v120
	v_mul_f32_e32 v122, v253, v253
	v_mul_f32_e32 v122, v122, v253
	v_fmamk_f32 v122, v122, 0x3d372713, v253
	v_mul_f32_e32 v122, 0xc0135761, v122
	v_exp_f32_e32 v122, v122
	s_nop 0
	v_add_f32_e32 v122, 1.0, v122
	v_rcp_f32_e32 v122, v122
	s_nop 0
	v_mul_f32_e32 v122, v122, v253
	v_mul_f32_e32 v253, v122, v121
